# attention: sum-guard softmax, variant without redo-once flag (alignment comparison)
# speedup vs baseline: 1.0823x; 1.0047x over previous
; #define LAS __attribute__((address_space(3)))
; #define wave (__builtin_amdgcn_readfirstlane((int)(threadIdx.x >> 6)))
; __device__ __forceinline__ void attn_phase(LAS unsigned char* lds, const bf16_t* __restrict__ Q, const bf16_t* __restrict__ KN, const bf16_t* __restrict__ KR,
;                                            const bf16_t* __restrict__ VT, bf16_t* AO, int vcu, int G, int tid, int lane, int wave) {
;     ...
;             const int bh = p >> 3, pp = p & 7, qb = half ? 15 - pp : pp, b = bh >> 3, h = bh & 7;
;             const size_t rowbase = (size_t)b * SEQ;
;             const int qrow0 = qb * 256 + wave * 32, qc = qrow0 >> 6, NT2 = 2 * qb + 2;
;             bf16x8 qf[6];
;             { const bf16_t* qp = Q + (rowbase + qrow0 + r32) * NQ + h * 96 + 8 * hi;
; #pragma unroll
;               for (int ks = 0; ks < 6; ++ks) qf[ks] = *(const bf16x8*)(qp + 16 * ks); }
;             const char* kbase = (const char*)(KN + rowbase * NKN + h * 64); const unsigned koff = (unsigned)(key_l * NKN + 8 * kc) * 2u;
;             const char* rbase = (const char*)(KR + rowbase * 32); const unsigned roff = (unsigned)(key_r * 32 + 8 * rc) * 2u;
;             const char* vbase = (const char*)(VT + (size_t)(h * 64) * MTOK + rowbase); const unsigned voff = (unsigned)((size_t)vd * MTOK + 8 * vc) * 2u;
;             const int kdst = (key_l * KP + 8 * kc) * 2, rdst = (key_r * KP + 64 + 8 * rc) * 2, vdst = KBUF + (vd * VP + 8 * vc) * 2;
;             u32x4 gk0, gk1, gr, gv0, gv1;
;             gk0 = *(const u32x4*)(kbase + koff); gk1 = *(const u32x4*)(kbase + 64 * NKN * 2 + koff); gr = *(const u32x4*)(rbase + roff); gv0 = *(const u32x4*)(vbase + voff); gv1 = *(const u32x4*)(vbase + 128 + voff);
;             *(LAS u32x4*)(lds + kdst) = gk0; *(LAS u32x4*)(lds + kdst + 64 * KP * 2) = gk1; *(LAS u32x4*)(lds + rdst) = gr; *(LAS u32x4*)(lds + vdst) = gv0; *(LAS u32x4*)(lds + vdst + 128) = gv1;
;             __syncthreads();
;             float m_run = -INFINITY, l_run = 0.f;
;             f32x16 o0, o1;
; #pragma unroll
;             for (int r = 0; r < 16; ++r) { o0[r] = 0.f; o1[r] = 0.f; }
.LBB0_533:
	s_xor_b64 s[12:13], s[6:7], -1
	s_and_b64 s[6:7], s[6:7], exec
	s_cselect_b32 s14, s23, s31
	s_lshl_b32 s6, s14, 8
	s_add_i32 s8, s6, s20
	v_lshl_add_u64 v[216:217], v[212:213], 0, s[8:9]
	s_lshl_b32 s36, s14, 1
	global_load_dwordx4 v[228:231], v198, s[10:11]
	s_add_u32 s14, s10, 0x10000
	s_addc_u32 s15, s11, 0
	v_mad_u64_u32 v[250:251], s[6:7], v216, s21, v[206:207]
	global_load_dwordx4 v[232:235], v198, s[14:15]
	v_mad_i32_i24 v251, v217, s21, v251
	global_load_dwordx4 v[236:239], v[208:209], off
	global_load_dwordx4 v[240:243], v[210:211], off
	global_load_dwordx4 v[244:247], v[210:211], off offset:128
	global_load_dwordx4 v[114:117], v[250:251], off
	global_load_dwordx4 v[118:121], v[250:251], off offset:32
	global_load_dwordx4 v[122:125], v[250:251], off offset:64
	global_load_dwordx4 v[126:129], v[250:251], off offset:96
	global_load_dwordx4 v[130:133], v[250:251], off offset:128
	global_load_dwordx4 v[134:137], v[250:251], off offset:160
	v_mov_b32_e32 v2, 0
	v_mov_b32_e32 v3, 0
	v_mov_b32_e32 v4, 0
	v_mov_b32_e32 v5, 0
	v_mov_b32_e32 v6, 0
	v_mov_b32_e32 v7, 0
	v_mov_b32_e32 v8, 0
	v_mov_b32_e32 v9, 0
	v_mov_b32_e32 v10, 0
	v_mov_b32_e32 v11, 0
	v_mov_b32_e32 v12, 0
	v_mov_b32_e32 v13, 0
	v_mov_b32_e32 v14, 0
	v_mov_b32_e32 v15, 0
	v_mov_b32_e32 v16, 0
	v_mov_b32_e32 v17, 0
	v_mov_b32_e32 v18, 0
	v_mov_b32_e32 v19, 0
	v_mov_b32_e32 v20, 0
	v_mov_b32_e32 v21, 0
	v_mov_b32_e32 v22, 0
	v_mov_b32_e32 v23, 0
	v_mov_b32_e32 v24, 0
	v_mov_b32_e32 v25, 0
	v_mov_b32_e32 v26, 0
	v_mov_b32_e32 v27, 0
	v_mov_b32_e32 v28, 0
	v_mov_b32_e32 v29, 0
	v_mov_b32_e32 v30, 0
	v_mov_b32_e32 v31, 0
	v_mov_b32_e32 v32, 0
	v_mov_b32_e32 v33, 0
	v_mov_b32_e32 v98, 0
	v_mov_b32_e32 v99, 0
	v_mov_b32_e32 v100, 0
	v_mov_b32_e32 v101, 0
	v_mov_b32_e32 v102, 0
	v_mov_b32_e32 v103, 0
	v_mov_b32_e32 v104, 0
	v_mov_b32_e32 v105, 0
	v_mov_b32_e32 v106, 0
	v_mov_b32_e32 v107, 0
	v_mov_b32_e32 v108, 0
	v_mov_b32_e32 v109, 0
	v_mov_b32_e32 v110, 0
	v_mov_b32_e32 v111, 0
	v_mov_b32_e32 v112, 0
	v_mov_b32_e32 v113, 0
	v_mov_b32_e32 v227, 0
	v_mov_b32_e32 v248, 0
	s_add_i32 s36, s36, 2
	s_lshr_b32 s33, s8, 6
	s_mov_b32 s8, 0
	s_mov_b32 s26, 0x4e800000
	s_mov_b32 s27, 0xff7fffff
	s_mov_b32 s6, 0
	s_mov_b32 s7, 1
	s_waitcnt vmcnt(6)
	s_mov_b32 s38, 0
	v_add_u32_e32 v1, s38, v219
	ds_write_b128 v1, v[228:231]
	ds_write_b128 v1, v[232:235] offset:13312
	v_add_u32_e32 v1, s38, v220
	ds_write_b128 v1, v[236:239]
	v_add_u32_e32 v1, s38, v221
	ds_write_b128 v1, v[240:243] offset:26624
	ds_write_b128 v1, v[244:247] offset:26752
	s_waitcnt lgkmcnt(0)
	s_barrier

; __device__ __forceinline__ float max3f(float a, float b, float c) { return fmaxf(fmaxf(a, b), c); }
; __device__ __forceinline__ void attn_softmax(f32x16& p0, f32x16& p1, bf16x8 (&pb)[4], f32x16& o0, f32x16& o1, float& m_run, float& l_run) {
;     float mx = max3f(p0[0], p0[1], p1[0]), my = max3f(p0[2], p0[3], p1[1]);
;     mx = max3f(mx, p1[2], p1[3]);
; #pragma unroll
;     for (int r = 4; r < 16; r += 4) { mx = max3f(mx, p0[r], p0[r + 1]); my = max3f(my, p0[r + 2], p0[r + 3]); mx = max3f(mx, p1[r], p1[r + 1]); my = max3f(my, p1[r + 2], p1[r + 3]); }
;     mx = fmaxf(mx, my);
;     { auto rr = __builtin_amdgcn_permlane32_swap(__float_as_uint(mx), __float_as_uint(mx), false, false); mx = fmaxf(__uint_as_float(rr[0]), __uint_as_float(rr[1])); }
;     const float m_new = fmaxf(m_run, mx);
;     const float alpha = __builtin_amdgcn_exp2f(m_run - m_new);
;     m_run = m_new;
;     p0 = p0 - m_new; p1 = p1 - m_new;
; #pragma unroll
;     for (int r = 0; r < 16; ++r) { p0[r] = __builtin_amdgcn_exp2f(p0[r]); p1[r] = __builtin_amdgcn_exp2f(p1[r]); }
;     f32x16 sm = p0 + p1;
;     f32x2v s2 = (f32x2v){sm[0], sm[1]} + (f32x2v){sm[2], sm[3]};
; #pragma unroll
;     for (int r = 4; r < 16; r += 2) s2 += (f32x2v){sm[r], sm[r + 1]};
;     l_run = l_run * alpha + (s2[0] + s2[1]);
; __device__ __forceinline__ void attn_phase(LAS unsigned char* lds, const bf16_t* __restrict__ Q, const bf16_t* __restrict__ KN, const bf16_t* __restrict__ KR,
;                                            const bf16_t* __restrict__ VT, bf16_t* AO, int vcu, int G, int tid, int lane, int wave) {
;     ...
;                     attn_ldk(kf, kA);
;                     __builtin_amdgcn_sched_barrier(0);
;                     attn_qk(a0, a1, kf, qf);
;                     attn_ldk(kf2, kA + 64 * KP * 2);
;                     __builtin_amdgcn_sched_barrier(0);
;                     attn_qk(b0, b1, kf2, qf);
;                     attn_softmax(a0, a1, pa, o0, o1, m_run, l_run);
.Lat_both:
	v_add_u32_e32 v1, s37, v222
	v_add_u32_e32 v225, s37, v223
	ds_read_b128 v[138:141], v1
	ds_read_b128 v[142:145], v1 offset:6656
	ds_read_b128 v[146:149], v1 offset:32
	ds_read_b128 v[150:153], v1 offset:6688
	ds_read_b128 v[154:157], v1 offset:64
	ds_read_b128 v[158:161], v1 offset:6720
	ds_read_b128 v[162:165], v1 offset:96
	ds_read_b128 v[166:169], v1 offset:6752
	s_waitcnt vmcnt(5)
	s_waitcnt lgkmcnt(7)
	v_mfma_f32_32x32x16_bf16 v[34:49], v[138:141], v[114:117], v[98:113]
	ds_read_b128 v[138:141], v1 offset:128
	s_waitcnt lgkmcnt(7)
	v_mfma_f32_32x32x16_bf16 v[50:65], v[142:145], v[114:117], v[98:113]
	ds_read_b128 v[142:145], v1 offset:6784
	s_waitcnt lgkmcnt(7)
	v_mfma_f32_32x32x16_bf16 v[34:49], v[146:149], v[118:121], v[34:49]
	ds_read_b128 v[146:149], v1 offset:160
	s_waitcnt lgkmcnt(7)
	v_mfma_f32_32x32x16_bf16 v[50:65], v[150:153], v[118:121], v[50:65]
	ds_read_b128 v[150:153], v1 offset:6816
	s_waitcnt lgkmcnt(7)
	v_mfma_f32_32x32x16_bf16 v[34:49], v[154:157], v[122:125], v[34:49]
	ds_read_b128 v[154:157], v1 offset:13312
	s_waitcnt lgkmcnt(7)
	v_mfma_f32_32x32x16_bf16 v[50:65], v[158:161], v[122:125], v[50:65]
	ds_read_b128 v[158:161], v1 offset:19968
	s_waitcnt lgkmcnt(7)
	v_mfma_f32_32x32x16_bf16 v[34:49], v[162:165], v[126:129], v[34:49]
	ds_read_b128 v[162:165], v1 offset:13344
	s_waitcnt lgkmcnt(7)
	v_mfma_f32_32x32x16_bf16 v[50:65], v[166:169], v[126:129], v[50:65]
	ds_read_b128 v[166:169], v1 offset:20000
	s_waitcnt lgkmcnt(7)
	v_mfma_f32_32x32x16_bf16 v[34:49], v[138:141], v[130:133], v[34:49]
	ds_read_b128 v[138:141], v1 offset:13376
	s_waitcnt lgkmcnt(7)
	v_mfma_f32_32x32x16_bf16 v[50:65], v[142:145], v[130:133], v[50:65]
	ds_read_b128 v[142:145], v1 offset:20032
	s_waitcnt lgkmcnt(7)
	v_mfma_f32_32x32x16_bf16 v[34:49], v[146:149], v[134:137], v[34:49]
	ds_read_b128 v[146:149], v1 offset:13408
	s_waitcnt lgkmcnt(7)
	v_mfma_f32_32x32x16_bf16 v[50:65], v[150:153], v[134:137], v[50:65]
	ds_read_b128 v[150:153], v1 offset:20064
	s_waitcnt lgkmcnt(7)
	v_mfma_f32_32x32x16_bf16 v[66:81], v[154:157], v[114:117], v[98:113]
	ds_read_b128 v[154:157], v1 offset:13440
	s_waitcnt lgkmcnt(7)
	v_mfma_f32_32x32x16_bf16 v[82:97], v[158:161], v[114:117], v[98:113]
	ds_read_b128 v[158:161], v1 offset:20096
	s_waitcnt lgkmcnt(7)
	v_mfma_f32_32x32x16_bf16 v[66:81], v[162:165], v[118:121], v[66:81]
	ds_read_b128 v[162:165], v1 offset:13472
	s_waitcnt lgkmcnt(7)
	v_mfma_f32_32x32x16_bf16 v[82:97], v[166:169], v[118:121], v[82:97]
	ds_read_b128 v[166:169], v1 offset:20128
	s_waitcnt lgkmcnt(7)
	v_mfma_f32_32x32x16_bf16 v[66:81], v[138:141], v[122:125], v[66:81]
	ds_read_b128 v[170:173], v225 offset:26624
	s_waitcnt lgkmcnt(7)
	v_mfma_f32_32x32x16_bf16 v[82:97], v[142:145], v[122:125], v[82:97]
	ds_read_b128 v[174:177], v225 offset:35328
	s_waitcnt lgkmcnt(7)
	v_mfma_f32_32x32x16_bf16 v[66:81], v[146:149], v[126:129], v[66:81]
	ds_read_b128 v[178:181], v225 offset:26656
	s_waitcnt lgkmcnt(7)
	v_mfma_f32_32x32x16_bf16 v[82:97], v[150:153], v[126:129], v[82:97]
	ds_read_b128 v[182:185], v225 offset:35360
	s_waitcnt lgkmcnt(7)
	v_mfma_f32_32x32x16_bf16 v[66:81], v[154:157], v[130:133], v[66:81]
	ds_read_b128 v[186:189], v225 offset:26688
	s_waitcnt lgkmcnt(7)
	v_mfma_f32_32x32x16_bf16 v[82:97], v[158:161], v[130:133], v[82:97]
	ds_read_b128 v[190:193], v225 offset:35392
	s_waitcnt lgkmcnt(7)
	v_mfma_f32_32x32x16_bf16 v[66:81], v[162:165], v[134:137], v[66:81]
	s_waitcnt lgkmcnt(6)
	v_mfma_f32_32x32x16_bf16 v[82:97], v[166:169], v[134:137], v[82:97]
	s_cmp_lg_u32 s7, 0
	s_cbranch_scc1 .Lat_first_A2
.Lat_exp_A2:
	v_exp_f32_e32 v34, v34
	v_exp_f32_e32 v50, v50
	v_exp_f32_e32 v35, v35
	v_exp_f32_e32 v51, v51
	v_exp_f32_e32 v36, v36
	v_exp_f32_e32 v52, v52
	v_exp_f32_e32 v37, v37
	v_exp_f32_e32 v53, v53
	v_exp_f32_e32 v38, v38
	v_exp_f32_e32 v54, v54
	v_exp_f32_e32 v39, v39
	v_exp_f32_e32 v55, v55
	v_exp_f32_e32 v40, v40
	v_exp_f32_e32 v56, v56
	v_exp_f32_e32 v41, v41
	v_exp_f32_e32 v57, v57
	v_exp_f32_e32 v42, v42
	v_exp_f32_e32 v58, v58
	v_exp_f32_e32 v43, v43
	v_exp_f32_e32 v59, v59
	v_exp_f32_e32 v44, v44
	v_exp_f32_e32 v60, v60
	v_exp_f32_e32 v45, v45
	v_exp_f32_e32 v61, v61
	v_exp_f32_e32 v46, v46
	v_exp_f32_e32 v62, v62
	v_exp_f32_e32 v47, v47
	v_exp_f32_e32 v63, v63
	v_exp_f32_e32 v48, v48
	v_exp_f32_e32 v64, v64
	v_exp_f32_e32 v49, v49
	v_exp_f32_e32 v65, v65
	v_pk_add_f32 v[250:251], v[34:35], v[36:37]
	v_pk_add_f32 v[252:253], v[50:51], v[52:53]
	v_pk_add_f32 v[250:251], v[250:251], v[38:39]
	v_pk_add_f32 v[252:253], v[252:253], v[54:55]
	v_pk_add_f32 v[250:251], v[250:251], v[40:41]
	v_pk_add_f32 v[252:253], v[252:253], v[56:57]
	v_pk_add_f32 v[250:251], v[250:251], v[42:43]
	v_pk_add_f32 v[252:253], v[252:253], v[58:59]
	v_pk_add_f32 v[250:251], v[250:251], v[44:45]
	v_pk_add_f32 v[252:253], v[252:253], v[60:61]
	v_pk_add_f32 v[250:251], v[250:251], v[46:47]
	v_pk_add_f32 v[252:253], v[252:253], v[62:63]
	v_pk_add_f32 v[250:251], v[250:251], v[48:49]
	v_pk_add_f32 v[252:253], v[252:253], v[64:65]
	v_pk_add_f32 v[250:251], v[250:251], v[252:253]
	v_add_f32_e32 v1, v250, v251
	v_cmp_lt_f32_e32 vcc, s26, v1
	s_cbranch_vccnz .Lat_rare_A2
; #define LAS __attribute__((address_space(3)))
; __device__ __forceinline__ void attn_phase(LAS unsigned char* lds, const bf16_t* __restrict__ Q, const bf16_t* __restrict__ KN, const bf16_t* __restrict__ KR,
;                                            const bf16_t* __restrict__ VT, bf16_t* AO, int vcu, int G, int tid, int lane, int wave) {
;     ...
;                     attn_softmax(a0, a1, pa, o0, o1, m_run, l_run);
;                     attn_ldv(vf, vA);
;                     __builtin_amdgcn_sched_barrier(0);
;                     PREFETCH_NEXT();
;                     attn_ldv(vf2, vA + 128);
;                     __builtin_amdgcn_sched_barrier(0);
;                     attn_pv(vf, pa, o0, o1);
;                     attn_softmax(b0, b1, pb2, o0, o1, m_run, l_run);
;                     __builtin_amdgcn_sched_barrier(0);
;                     attn_pv(vf2, pb2, o0, o1);
;     ...
;                 if (more) { LAS unsigned char* nb = lds + ((t + 1) & 1) * BUF;
;                     *(LAS u32x4*)(nb + kdst) = gk0; *(LAS u32x4*)(nb + kdst + 64 * KP * 2) = gk1; *(LAS u32x4*)(nb + rdst) = gr; *(LAS u32x4*)(nb + vdst) = gv0; *(LAS u32x4*)(nb + vdst + 128) = gv1; }
.Lat_fast_A2:
	v_add_f32_e32 v227, v227, v1
	v_cvt_pk_bf16_f32 v34, v34, v35
	v_cvt_pk_bf16_f32 v35, v36, v37
	v_cvt_pk_bf16_f32 v36, v38, v39
	v_cvt_pk_bf16_f32 v37, v40, v41
	v_cvt_pk_bf16_f32 v42, v42, v43
	v_cvt_pk_bf16_f32 v43, v44, v45
	v_cvt_pk_bf16_f32 v44, v46, v47
	v_cvt_pk_bf16_f32 v45, v48, v49
	v_cvt_pk_bf16_f32 v50, v50, v51
	v_cvt_pk_bf16_f32 v51, v52, v53
	v_cvt_pk_bf16_f32 v52, v54, v55
	v_cvt_pk_bf16_f32 v53, v56, v57
	v_cvt_pk_bf16_f32 v58, v58, v59
	v_cvt_pk_bf16_f32 v59, v60, v61
	v_cvt_pk_bf16_f32 v60, v62, v63
	v_cvt_pk_bf16_f32 v61, v64, v65
	s_waitcnt lgkmcnt(5)
	v_mfma_f32_32x32x16_bf16 v[2:17], v[170:173], v[34:37], v[2:17]
	ds_read_b128 v[170:173], v225 offset:26720
	s_waitcnt lgkmcnt(5)
	v_mfma_f32_32x32x16_bf16 v[18:33], v[174:177], v[34:37], v[18:33]
	ds_read_b128 v[174:177], v225 offset:35424
	s_waitcnt vmcnt(0)
	v_add_u32_e32 v226, s38, v219
	ds_write_b128 v226, v[228:231]
	s_waitcnt lgkmcnt(6)
	v_mfma_f32_32x32x16_bf16 v[2:17], v[178:181], v[42:45], v[2:17]
	ds_read_b128 v[178:181], v225 offset:26752
	ds_write_b128 v226, v[232:235] offset:13312
	s_waitcnt lgkmcnt(7)
	v_mfma_f32_32x32x16_bf16 v[18:33], v[182:185], v[42:45], v[18:33]
	ds_read_b128 v[182:185], v225 offset:35456
	v_add_u32_e32 v226, s38, v220
	ds_write_b128 v226, v[236:239]
	s_waitcnt lgkmcnt(8)
	v_mfma_f32_32x32x16_bf16 v[2:17], v[186:189], v[50:53], v[2:17]
	ds_read_b128 v[186:189], v225 offset:26784
	v_add_u32_e32 v226, s38, v221
	ds_write_b128 v226, v[240:243] offset:26624
	s_waitcnt lgkmcnt(9)
	v_mfma_f32_32x32x16_bf16 v[18:33], v[190:193], v[50:53], v[18:33]
	ds_read_b128 v[190:193], v225 offset:35488
	ds_write_b128 v226, v[244:247] offset:26752
	s_waitcnt lgkmcnt(10)
	v_mfma_f32_32x32x16_bf16 v[2:17], v[170:173], v[58:61], v[2:17]
	ds_read_b128 v[170:173], v225 offset:26816
	s_waitcnt lgkmcnt(10)
	v_mfma_f32_32x32x16_bf16 v[18:33], v[174:177], v[58:61], v[18:33]
	ds_read_b128 v[174:177], v225 offset:35520
	s_cmp_lg_u32 s6, 0
	s_cbranch_scc1 .Lat_fix_B
.Lat_fixed_B:
	s_cmp_lg_u32 s7, 0
	s_cbranch_scc1 .Lat_first_B2
.Lat_exp_B2:
	v_exp_f32_e32 v66, v66
	v_exp_f32_e32 v82, v82
	v_exp_f32_e32 v67, v67
	v_exp_f32_e32 v83, v83
	v_exp_f32_e32 v68, v68
	v_exp_f32_e32 v84, v84
	v_exp_f32_e32 v69, v69
	v_exp_f32_e32 v85, v85
	v_exp_f32_e32 v70, v70
	v_exp_f32_e32 v86, v86
	v_exp_f32_e32 v71, v71
	v_exp_f32_e32 v87, v87
	v_exp_f32_e32 v72, v72
	v_exp_f32_e32 v88, v88
	v_exp_f32_e32 v73, v73
	v_exp_f32_e32 v89, v89
	v_exp_f32_e32 v74, v74
	v_exp_f32_e32 v90, v90
	v_exp_f32_e32 v75, v75
	v_exp_f32_e32 v91, v91
	v_exp_f32_e32 v76, v76
	v_exp_f32_e32 v92, v92
	v_exp_f32_e32 v77, v77
	v_exp_f32_e32 v93, v93
	v_exp_f32_e32 v78, v78
	v_exp_f32_e32 v94, v94
	v_exp_f32_e32 v79, v79
	v_exp_f32_e32 v95, v95
	v_exp_f32_e32 v80, v80
	v_exp_f32_e32 v96, v96
	v_exp_f32_e32 v81, v81
	v_exp_f32_e32 v97, v97
	v_pk_add_f32 v[250:251], v[66:67], v[68:69]
	v_pk_add_f32 v[252:253], v[82:83], v[84:85]
	v_pk_add_f32 v[250:251], v[250:251], v[70:71]
	v_pk_add_f32 v[252:253], v[252:253], v[86:87]
	v_pk_add_f32 v[250:251], v[250:251], v[72:73]
	v_pk_add_f32 v[252:253], v[252:253], v[88:89]
	v_pk_add_f32 v[250:251], v[250:251], v[74:75]
	v_pk_add_f32 v[252:253], v[252:253], v[90:91]
	v_pk_add_f32 v[250:251], v[250:251], v[76:77]
	v_pk_add_f32 v[252:253], v[252:253], v[92:93]
	v_pk_add_f32 v[250:251], v[250:251], v[78:79]
	v_pk_add_f32 v[252:253], v[252:253], v[94:95]
	v_pk_add_f32 v[250:251], v[250:251], v[80:81]
	v_pk_add_f32 v[252:253], v[252:253], v[96:97]
	v_pk_add_f32 v[250:251], v[250:251], v[252:253]
	v_add_f32_e32 v1, v250, v251
	v_cmp_lt_f32_e32 vcc, s26, v1
	s_cbranch_vccnz .Lat_rare_B2
.Lat_fast_B2:
	v_add_f32_e32 v227, v227, v1
	v_cvt_pk_bf16_f32 v66, v66, v67
	v_cvt_pk_bf16_f32 v67, v68, v69
	v_cvt_pk_bf16_f32 v68, v70, v71
	v_cvt_pk_bf16_f32 v69, v72, v73
	v_cvt_pk_bf16_f32 v74, v74, v75
	v_cvt_pk_bf16_f32 v75, v76, v77
	v_cvt_pk_bf16_f32 v76, v78, v79
	v_cvt_pk_bf16_f32 v77, v80, v81
	v_cvt_pk_bf16_f32 v82, v82, v83
	v_cvt_pk_bf16_f32 v83, v84, v85
	v_cvt_pk_bf16_f32 v84, v86, v87
	v_cvt_pk_bf16_f32 v85, v88, v89
	v_cvt_pk_bf16_f32 v90, v90, v91
	v_cvt_pk_bf16_f32 v91, v92, v93
	v_cvt_pk_bf16_f32 v92, v94, v95
	v_cvt_pk_bf16_f32 v93, v96, v97
	s_waitcnt lgkmcnt(9)
	v_mfma_f32_32x32x16_bf16 v[2:17], v[178:181], v[66:69], v[2:17]
	ds_read_b128 v[178:181], v225 offset:26848
	s_waitcnt lgkmcnt(8)
	v_mfma_f32_32x32x16_bf16 v[18:33], v[182:185], v[66:69], v[18:33]
	ds_read_b128 v[182:185], v225 offset:35552
	s_waitcnt lgkmcnt(7)
	v_mfma_f32_32x32x16_bf16 v[2:17], v[186:189], v[74:77], v[2:17]
	s_waitcnt lgkmcnt(5)
	v_mfma_f32_32x32x16_bf16 v[18:33], v[190:193], v[74:77], v[18:33]
	s_waitcnt lgkmcnt(3)
	v_mfma_f32_32x32x16_bf16 v[2:17], v[170:173], v[82:85], v[2:17]
	s_waitcnt lgkmcnt(2)
	v_mfma_f32_32x32x16_bf16 v[18:33], v[174:177], v[82:85], v[18:33]
	s_waitcnt lgkmcnt(1)
	v_mfma_f32_32x32x16_bf16 v[2:17], v[178:181], v[90:93], v[2:17]
	s_waitcnt lgkmcnt(0)
	v_mfma_f32_32x32x16_bf16 v[18:33], v[182:185], v[90:93], v[18:33]
	s_branch .Lat_nostage
; __device__ __forceinline__ float max3f(float a, float b, float c) { return fmaxf(fmaxf(a, b), c); }
; __device__ __forceinline__ void attn_softmax(f32x16& p0, f32x16& p1, bf16x8 (&pb)[4], f32x16& o0, f32x16& o1, float& m_run, float& l_run) {
;     float mx = max3f(p0[0], p0[1], p1[0]), my = max3f(p0[2], p0[3], p1[1]);
;     mx = max3f(mx, p1[2], p1[3]);
; #pragma unroll
;     for (int r = 4; r < 16; r += 4) { mx = max3f(mx, p0[r], p0[r + 1]); my = max3f(my, p0[r + 2], p0[r + 3]); mx = max3f(mx, p1[r], p1[r + 1]); my = max3f(my, p1[r + 2], p1[r + 3]); }
;     mx = fmaxf(mx, my);
;     { auto rr = __builtin_amdgcn_permlane32_swap(__float_as_uint(mx), __float_as_uint(mx), false, false); mx = fmaxf(__uint_as_float(rr[0]), __uint_as_float(rr[1])); }
;     const float m_new = fmaxf(m_run, mx);
;     const float alpha = __builtin_amdgcn_exp2f(m_run - m_new);
;     m_run = m_new;
;     p0 = p0 - m_new; p1 = p1 - m_new;
; #pragma unroll
;     for (int r = 0; r < 16; ++r) { p0[r] = __builtin_amdgcn_exp2f(p0[r]); p1[r] = __builtin_amdgcn_exp2f(p1[r]); }
;     f32x16 sm = p0 + p1;
;     f32x2v s2 = (f32x2v){sm[0], sm[1]} + (f32x2v){sm[2], sm[3]};
; #pragma unroll
;     for (int r = 4; r < 16; r += 2) s2 += (f32x2v){sm[r], sm[r + 1]};
;     l_run = l_run * alpha + (s2[0] + s2[1]);
; __device__ __forceinline__ void attn_phase(LAS unsigned char* lds, const bf16_t* __restrict__ Q, const bf16_t* __restrict__ KN, const bf16_t* __restrict__ KR,
;                                            const bf16_t* __restrict__ VT, bf16_t* AO, int vcu, int G, int tid, int lane, int wave) {
;     ...
;                     bf16x8 kf[12], vf[8], pa[4]; f32x16 a0, a1;
;                     PREFETCH_NEXT();
;                     attn_ldk(kf, kA);
;                     __builtin_amdgcn_sched_barrier(0);
;                     attn_qk(a0, a1, kf, qf);
;                     __builtin_amdgcn_sched_barrier(0);
;                     attn_ldv(vf, vA);
;                     __builtin_amdgcn_sched_barrier(0);
;                     attn_softmax(a0, a1, pa, o0, o1, m_run, l_run);
;                     __builtin_amdgcn_sched_barrier(0);
;                     attn_pv(vf, pa, o0, o1);
.Lat_single:
	v_add_u32_e32 v1, s37, v222
	v_add_u32_e32 v225, s37, v223
	ds_read_b128 v[138:141], v1
	ds_read_b128 v[142:145], v1 offset:6656
	ds_read_b128 v[146:149], v1 offset:32
	ds_read_b128 v[150:153], v1 offset:6688
	ds_read_b128 v[154:157], v1 offset:64
	ds_read_b128 v[158:161], v1 offset:6720
	ds_read_b128 v[162:165], v1 offset:96
	ds_read_b128 v[166:169], v1 offset:6752
	s_waitcnt vmcnt(5)
	s_waitcnt lgkmcnt(7)
	v_mfma_f32_32x32x16_bf16 v[34:49], v[138:141], v[114:117], v[98:113]
	ds_read_b128 v[138:141], v1 offset:128
	s_waitcnt lgkmcnt(7)
	v_mfma_f32_32x32x16_bf16 v[50:65], v[142:145], v[114:117], v[98:113]
	ds_read_b128 v[142:145], v1 offset:6784
	s_waitcnt lgkmcnt(7)
	v_mfma_f32_32x32x16_bf16 v[34:49], v[146:149], v[118:121], v[34:49]
	ds_read_b128 v[146:149], v1 offset:160
	s_waitcnt lgkmcnt(7)
	v_mfma_f32_32x32x16_bf16 v[50:65], v[150:153], v[118:121], v[50:65]
	ds_read_b128 v[150:153], v1 offset:6816
	s_waitcnt lgkmcnt(7)
	v_mfma_f32_32x32x16_bf16 v[34:49], v[154:157], v[122:125], v[34:49]
	ds_read_b128 v[170:173], v225 offset:26624
	s_waitcnt lgkmcnt(7)
	v_mfma_f32_32x32x16_bf16 v[50:65], v[158:161], v[122:125], v[50:65]
	ds_read_b128 v[174:177], v225 offset:35328
	s_waitcnt lgkmcnt(7)
	v_mfma_f32_32x32x16_bf16 v[34:49], v[162:165], v[126:129], v[34:49]
	ds_read_b128 v[178:181], v225 offset:26656
	s_waitcnt lgkmcnt(7)
	v_mfma_f32_32x32x16_bf16 v[50:65], v[166:169], v[126:129], v[50:65]
	ds_read_b128 v[182:185], v225 offset:35360
	s_waitcnt lgkmcnt(7)
	v_mfma_f32_32x32x16_bf16 v[34:49], v[138:141], v[130:133], v[34:49]
	ds_read_b128 v[186:189], v225 offset:26688
	s_waitcnt lgkmcnt(7)
	v_mfma_f32_32x32x16_bf16 v[50:65], v[142:145], v[130:133], v[50:65]
	ds_read_b128 v[190:193], v225 offset:35392
	s_waitcnt lgkmcnt(7)
	v_mfma_f32_32x32x16_bf16 v[34:49], v[146:149], v[134:137], v[34:49]
	s_waitcnt lgkmcnt(6)
	v_mfma_f32_32x32x16_bf16 v[50:65], v[150:153], v[134:137], v[50:65]
	s_cmp_lg_u32 s7, 0
	s_cbranch_scc1 .Lat_first_A1
.Lat_exp_A1:
	s_nop 7
	v_exp_f32_e32 v34, v34
	s_nop 0
	v_exp_f32_e32 v50, v50
	v_exp_f32_e32 v35, v35
	v_exp_f32_e32 v51, v51
	v_exp_f32_e32 v36, v36
	v_exp_f32_e32 v52, v52
	v_exp_f32_e32 v37, v37
	v_exp_f32_e32 v53, v53
	v_exp_f32_e32 v38, v38
	v_exp_f32_e32 v54, v54
	v_exp_f32_e32 v39, v39
	v_exp_f32_e32 v55, v55
	v_exp_f32_e32 v40, v40
	v_exp_f32_e32 v56, v56
	v_exp_f32_e32 v41, v41
	v_exp_f32_e32 v57, v57
	v_exp_f32_e32 v42, v42
	v_exp_f32_e32 v58, v58
	v_exp_f32_e32 v43, v43
	v_exp_f32_e32 v59, v59
	v_exp_f32_e32 v44, v44
	v_exp_f32_e32 v60, v60
	v_exp_f32_e32 v45, v45
	v_exp_f32_e32 v61, v61
	v_exp_f32_e32 v46, v46
	v_exp_f32_e32 v62, v62
	v_exp_f32_e32 v47, v47
	v_exp_f32_e32 v63, v63
	v_exp_f32_e32 v48, v48
	v_exp_f32_e32 v64, v64
	v_exp_f32_e32 v49, v49
	v_exp_f32_e32 v65, v65
	v_pk_add_f32 v[250:251], v[34:35], v[36:37]
	v_pk_add_f32 v[252:253], v[50:51], v[52:53]
	v_pk_add_f32 v[250:251], v[250:251], v[38:39]
	v_pk_add_f32 v[252:253], v[252:253], v[54:55]
	v_pk_add_f32 v[250:251], v[250:251], v[40:41]
	v_pk_add_f32 v[252:253], v[252:253], v[56:57]
	v_pk_add_f32 v[250:251], v[250:251], v[42:43]
	v_pk_add_f32 v[252:253], v[252:253], v[58:59]
	v_pk_add_f32 v[250:251], v[250:251], v[44:45]
	v_pk_add_f32 v[252:253], v[252:253], v[60:61]
	v_pk_add_f32 v[250:251], v[250:251], v[46:47]
	v_pk_add_f32 v[252:253], v[252:253], v[62:63]
	v_pk_add_f32 v[250:251], v[250:251], v[48:49]
	v_pk_add_f32 v[252:253], v[252:253], v[64:65]
	v_pk_add_f32 v[250:251], v[250:251], v[252:253]
	v_add_f32_e32 v1, v250, v251
	v_cmp_lt_f32_e32 vcc, s26, v1
	s_cbranch_vccnz .Lat_rare_A1
.Lat_fast_A1:
	v_add_f32_e32 v227, v227, v1
	v_cvt_pk_bf16_f32 v34, v34, v35
	v_cvt_pk_bf16_f32 v35, v36, v37
	v_cvt_pk_bf16_f32 v36, v38, v39
	v_cvt_pk_bf16_f32 v37, v40, v41
	v_cvt_pk_bf16_f32 v42, v42, v43
	v_cvt_pk_bf16_f32 v43, v44, v45
	v_cvt_pk_bf16_f32 v44, v46, v47
	v_cvt_pk_bf16_f32 v45, v48, v49
	v_cvt_pk_bf16_f32 v50, v50, v51
	v_cvt_pk_bf16_f32 v51, v52, v53
	v_cvt_pk_bf16_f32 v52, v54, v55
	v_cvt_pk_bf16_f32 v53, v56, v57
	v_cvt_pk_bf16_f32 v58, v58, v59
	v_cvt_pk_bf16_f32 v59, v60, v61
	v_cvt_pk_bf16_f32 v60, v62, v63
	v_cvt_pk_bf16_f32 v61, v64, v65
	s_waitcnt lgkmcnt(5)
	v_mfma_f32_32x32x16_bf16 v[2:17], v[170:173], v[34:37], v[2:17]
	ds_read_b128 v[170:173], v225 offset:26720
	s_waitcnt lgkmcnt(5)
	v_mfma_f32_32x32x16_bf16 v[18:33], v[174:177], v[34:37], v[18:33]
	ds_read_b128 v[174:177], v225 offset:35424
	s_waitcnt lgkmcnt(5)
	v_mfma_f32_32x32x16_bf16 v[2:17], v[178:181], v[42:45], v[2:17]
	s_waitcnt lgkmcnt(4)
	v_mfma_f32_32x32x16_bf16 v[18:33], v[182:185], v[42:45], v[18:33]
	s_waitcnt lgkmcnt(3)
	v_mfma_f32_32x32x16_bf16 v[2:17], v[186:189], v[50:53], v[2:17]
	s_waitcnt lgkmcnt(2)
	v_mfma_f32_32x32x16_bf16 v[18:33], v[190:193], v[50:53], v[18:33]
	s_waitcnt lgkmcnt(1)
	v_mfma_f32_32x32x16_bf16 v[2:17], v[170:173], v[58:61], v[2:17]
	s_waitcnt lgkmcnt(0)
	v_mfma_f32_32x32x16_bf16 v[18:33], v[174:177], v[58:61], v[18:33]

; __device__ __forceinline__ float max3f(float a, float b, float c) { return fmaxf(fmaxf(a, b), c); }
; __device__ __forceinline__ void attn_softmax(f32x16& p0, f32x16& p1, bf16x8 (&pb)[4], f32x16& o0, f32x16& o1, float& m_run, float& l_run) {
;     float mx = max3f(p0[0], p0[1], p1[0]), my = max3f(p0[2], p0[3], p1[1]);
;     mx = max3f(mx, p1[2], p1[3]);
; #pragma unroll
;     for (int r = 4; r < 16; r += 4) { mx = max3f(mx, p0[r], p0[r + 1]); my = max3f(my, p0[r + 2], p0[r + 3]); mx = max3f(mx, p1[r], p1[r + 1]); my = max3f(my, p1[r + 2], p1[r + 3]); }
;     mx = fmaxf(mx, my);
;     { auto rr = __builtin_amdgcn_permlane32_swap(__float_as_uint(mx), __float_as_uint(mx), false, false); mx = fmaxf(__uint_as_float(rr[0]), __uint_as_float(rr[1])); }
;     const float m_new = fmaxf(m_run, mx);
;     const float alpha = __builtin_amdgcn_exp2f(m_run - m_new);
;     m_run = m_new;
;     p0 = p0 - m_new; p1 = p1 - m_new;
; #pragma unroll
;     for (int r = 0; r < 16; ++r) { p0[r] = __builtin_amdgcn_exp2f(p0[r]); p1[r] = __builtin_amdgcn_exp2f(p1[r]); }
;     f32x16 sm = p0 + p1;
;     f32x2v s2 = (f32x2v){sm[0], sm[1]} + (f32x2v){sm[2], sm[3]};
; #pragma unroll
;     for (int r = 4; r < 16; r += 2) s2 += (f32x2v){sm[r], sm[r + 1]};
;     l_run = l_run * alpha + (s2[0] + s2[1]);
;     o0 = o0 * alpha; o1 = o1 * alpha;
.Lat_first_A2:
	s_nop 15
	v_max3_f32 v249, v34, v35, v36
	v_max3_f32 v1, v50, v51, v52
	v_max3_f32 v249, v249, v37, v38
	v_max3_f32 v1, v1, v53, v54
	v_max3_f32 v249, v249, v39, v40
	v_max3_f32 v1, v1, v55, v56
	v_max3_f32 v249, v249, v41, v42
	v_max3_f32 v1, v1, v57, v58
	v_max3_f32 v249, v249, v43, v44
	v_max3_f32 v1, v1, v59, v60
	v_max3_f32 v249, v249, v45, v46
	v_max3_f32 v1, v1, v61, v62
	v_max3_f32 v249, v249, v47, v48
	v_max3_f32 v1, v1, v63, v64
	v_max_f32_e32 v249, v249, v49
	v_max_f32_e32 v1, v1, v65
	v_max_f32_e32 v249, v249, v1
	v_mov_b32_e32 v1, v249
	s_nop 1
	v_permlane32_swap_b32_e32 v249, v1
	v_max_f32_e32 v249, v249, v1
	v_max_f32_e32 v250, s27, v249
	v_add_f32_e32 v248, v248, v250
	v_sub_f32_e32 v251, 0, v248
	v_mov_b32_e32 v98, v251
	v_mov_b32_e32 v99, v251
	v_mov_b32_e32 v100, v251
	v_mov_b32_e32 v101, v251
	v_mov_b32_e32 v102, v251
	v_mov_b32_e32 v103, v251
	v_mov_b32_e32 v104, v251
	v_mov_b32_e32 v105, v251
	v_mov_b32_e32 v106, v251
	v_mov_b32_e32 v107, v251
	v_mov_b32_e32 v108, v251
	v_mov_b32_e32 v109, v251
	v_mov_b32_e32 v110, v251
	v_mov_b32_e32 v111, v251
	v_mov_b32_e32 v112, v251
	v_mov_b32_e32 v113, v251
	v_sub_f32_e32 v34, v34, v250
	v_sub_f32_e32 v35, v35, v250
	v_sub_f32_e32 v36, v36, v250
	v_sub_f32_e32 v37, v37, v250
	v_sub_f32_e32 v38, v38, v250
	v_sub_f32_e32 v39, v39, v250
	v_sub_f32_e32 v40, v40, v250
	v_sub_f32_e32 v41, v41, v250
	v_sub_f32_e32 v42, v42, v250
	v_sub_f32_e32 v43, v43, v250
	v_sub_f32_e32 v44, v44, v250
	v_sub_f32_e32 v45, v45, v250
	v_sub_f32_e32 v46, v46, v250
	v_sub_f32_e32 v47, v47, v250
	v_sub_f32_e32 v48, v48, v250
	v_sub_f32_e32 v49, v49, v250
	v_sub_f32_e32 v50, v50, v250
	v_sub_f32_e32 v51, v51, v250
	v_sub_f32_e32 v52, v52, v250
	v_sub_f32_e32 v53, v53, v250
	v_sub_f32_e32 v54, v54, v250
	v_sub_f32_e32 v55, v55, v250
	v_sub_f32_e32 v56, v56, v250
	v_sub_f32_e32 v57, v57, v250
	v_sub_f32_e32 v58, v58, v250
	v_sub_f32_e32 v59, v59, v250
	v_sub_f32_e32 v60, v60, v250
	v_sub_f32_e32 v61, v61, v250
	v_sub_f32_e32 v62, v62, v250
	v_sub_f32_e32 v63, v63, v250
	v_sub_f32_e32 v64, v64, v250
	v_sub_f32_e32 v65, v65, v250
	v_sub_f32_e32 v252, 0, v250
	v_min_f32_e32 v252, 0x42800000, v252
	v_exp_f32_e32 v252, v252
	s_mov_b32 s7, 0
	s_mov_b32 s27, 0
	v_mul_f32_e32 v227, v227, v252
	v_mul_f32_e32 v2, v2, v252
	v_mul_f32_e32 v3, v3, v252
	v_mul_f32_e32 v4, v4, v252
	v_mul_f32_e32 v5, v5, v252
	v_mul_f32_e32 v6, v6, v252
	v_mul_f32_e32 v7, v7, v252
	v_mul_f32_e32 v8, v8, v252
	v_mul_f32_e32 v9, v9, v252
	v_mul_f32_e32 v10, v10, v252
	v_mul_f32_e32 v11, v11, v252
	v_mul_f32_e32 v12, v12, v252
	v_mul_f32_e32 v13, v13, v252
	v_mul_f32_e32 v14, v14, v252
	v_mul_f32_e32 v15, v15, v252
	v_mul_f32_e32 v16, v16, v252
	v_mul_f32_e32 v17, v17, v252
	v_mul_f32_e32 v18, v18, v252
	v_mul_f32_e32 v19, v19, v252
	v_mul_f32_e32 v20, v20, v252
	v_mul_f32_e32 v21, v21, v252
	v_mul_f32_e32 v22, v22, v252
	v_mul_f32_e32 v23, v23, v252
	v_mul_f32_e32 v24, v24, v252
	v_mul_f32_e32 v25, v25, v252
	v_mul_f32_e32 v26, v26, v252
	v_mul_f32_e32 v27, v27, v252
	v_mul_f32_e32 v28, v28, v252
	v_mul_f32_e32 v29, v29, v252
	v_mul_f32_e32 v30, v30, v252
	v_mul_f32_e32 v31, v31, v252
	v_mul_f32_e32 v32, v32, v252
	v_mul_f32_e32 v33, v33, v252
	v_mov_b32_e32 v218, v250
	s_mov_b32 s6, 1
	s_nop 1
	s_branch .Lat_exp_A2
.Lat_rare_A2:
	s_nop 15
	v_cmp_lt_f32_e32 vcc, 0x71800000, v1
	s_cbranch_vccnz .Lat_redo_A2
	v_frexp_exp_i32_f32_e32 v250, v1
	v_max_i32_e32 v250, 0, v250
	v_mov_b32_e32 v251, v250
	s_nop 1
	v_permlane32_swap_b32_e32 v250, v251
	v_max_i32_e32 v250, v250, v251
	v_sub_u32_e32 v251, 0, v250
	v_ldexp_f32 v34, v34, v251
	v_ldexp_f32 v35, v35, v251
	v_ldexp_f32 v36, v36, v251
	v_ldexp_f32 v37, v37, v251
	v_ldexp_f32 v38, v38, v251
	v_ldexp_f32 v39, v39, v251
	v_ldexp_f32 v40, v40, v251
	v_ldexp_f32 v41, v41, v251
	v_ldexp_f32 v42, v42, v251
	v_ldexp_f32 v43, v43, v251
	v_ldexp_f32 v44, v44, v251
	v_ldexp_f32 v45, v45, v251
	v_ldexp_f32 v46, v46, v251
	v_ldexp_f32 v47, v47, v251
	v_ldexp_f32 v48, v48, v251
	v_ldexp_f32 v49, v49, v251
	v_ldexp_f32 v50, v50, v251
	v_ldexp_f32 v51, v51, v251
	v_ldexp_f32 v52, v52, v251
	v_ldexp_f32 v53, v53, v251
	v_ldexp_f32 v54, v54, v251
	v_ldexp_f32 v55, v55, v251
	v_ldexp_f32 v56, v56, v251
	v_ldexp_f32 v57, v57, v251
	v_ldexp_f32 v58, v58, v251
	v_ldexp_f32 v59, v59, v251
	v_ldexp_f32 v60, v60, v251
	v_ldexp_f32 v61, v61, v251
	v_ldexp_f32 v62, v62, v251
	v_ldexp_f32 v63, v63, v251
	v_ldexp_f32 v64, v64, v251
	v_ldexp_f32 v65, v65, v251
	v_ldexp_f32 v1, v1, v251
	v_ldexp_f32 v227, v227, v251
	v_ldexp_f32 v2, v2, v251
	v_ldexp_f32 v3, v3, v251
	v_ldexp_f32 v4, v4, v251
	v_ldexp_f32 v5, v5, v251
	v_ldexp_f32 v6, v6, v251
	v_ldexp_f32 v7, v7, v251
	v_ldexp_f32 v8, v8, v251
	v_ldexp_f32 v9, v9, v251
	v_ldexp_f32 v10, v10, v251
	v_ldexp_f32 v11, v11, v251
	v_ldexp_f32 v12, v12, v251
	v_ldexp_f32 v13, v13, v251
	v_ldexp_f32 v14, v14, v251
	v_ldexp_f32 v15, v15, v251
	v_ldexp_f32 v16, v16, v251
	v_ldexp_f32 v17, v17, v251
	v_ldexp_f32 v18, v18, v251
	v_ldexp_f32 v19, v19, v251
	v_ldexp_f32 v20, v20, v251
	v_ldexp_f32 v21, v21, v251
	v_ldexp_f32 v22, v22, v251
	v_ldexp_f32 v23, v23, v251
	v_ldexp_f32 v24, v24, v251
	v_ldexp_f32 v25, v25, v251
	v_ldexp_f32 v26, v26, v251
	v_ldexp_f32 v27, v27, v251
	v_ldexp_f32 v28, v28, v251
	v_ldexp_f32 v29, v29, v251
	v_ldexp_f32 v30, v30, v251
	v_ldexp_f32 v31, v31, v251
	v_ldexp_f32 v32, v32, v251
	v_ldexp_f32 v33, v33, v251
	v_cvt_f32_i32_e32 v252, v250
	v_add_f32_e32 v248, v248, v252
	v_sub_f32_e32 v253, 0, v248
	v_mov_b32_e32 v98, v253
	v_mov_b32_e32 v99, v253
	v_mov_b32_e32 v100, v253
	v_mov_b32_e32 v101, v253
	v_mov_b32_e32 v102, v253
	v_mov_b32_e32 v103, v253
	v_mov_b32_e32 v104, v253
	v_mov_b32_e32 v105, v253
	v_mov_b32_e32 v106, v253
	v_mov_b32_e32 v107, v253
	v_mov_b32_e32 v108, v253
	v_mov_b32_e32 v109, v253
	v_mov_b32_e32 v110, v253
	v_mov_b32_e32 v111, v253
	v_mov_b32_e32 v112, v253
	v_mov_b32_e32 v113, v253
	v_mov_b32_e32 v218, v252
	s_mov_b32 s6, 1
	s_nop 1
	s_branch .Lat_fast_A2
; __device__ __forceinline__ float max3f(float a, float b, float c) { return fmaxf(fmaxf(a, b), c); }
; __device__ __forceinline__ void attn_qk(f32x16& p0, f32x16& p1, const bf16x8 (&kf)[12], const bf16x8 (&qf)[6]) {
;     const f32x16 zero = {0.f, 0.f, 0.f, 0.f, 0.f, 0.f, 0.f, 0.f, 0.f, 0.f, 0.f, 0.f, 0.f, 0.f, 0.f, 0.f};
; #pragma unroll
;     for (int ks = 0; ks < 6; ++ks) {
;         p0 = __builtin_amdgcn_mfma_f32_32x32x16_bf16(kf[2 * ks], qf[ks], ks == 0 ? zero : p0, 0, 0, 0);
;         p1 = __builtin_amdgcn_mfma_f32_32x32x16_bf16(kf[2 * ks + 1], qf[ks], ks == 0 ? zero : p1, 0, 0, 0);
;     }
; }
; __device__ __forceinline__ void attn_softmax(f32x16& p0, f32x16& p1, bf16x8 (&pb)[4], f32x16& o0, f32x16& o1, float& m_run, float& l_run) {
;     float mx = max3f(p0[0], p0[1], p1[0]), my = max3f(p0[2], p0[3], p1[1]);
;     mx = max3f(mx, p1[2], p1[3]);
; #pragma unroll
;     for (int r = 4; r < 16; r += 4) { mx = max3f(mx, p0[r], p0[r + 1]); my = max3f(my, p0[r + 2], p0[r + 3]); mx = max3f(mx, p1[r], p1[r + 1]); my = max3f(my, p1[r + 2], p1[r + 3]); }
;     mx = fmaxf(mx, my);
;     { auto rr = __builtin_amdgcn_permlane32_swap(__float_as_uint(mx), __float_as_uint(mx), false, false); mx = fmaxf(__uint_as_float(rr[0]), __uint_as_float(rr[1])); }
;     const float m_new = fmaxf(m_run, mx);
;     const float alpha = __builtin_amdgcn_exp2f(m_run - m_new);
;     m_run = m_new;
;     p0 = p0 - m_new; p1 = p1 - m_new;
; #pragma unroll
;     for (int r = 0; r < 16; ++r) { p0[r] = __builtin_amdgcn_exp2f(p0[r]); p1[r] = __builtin_amdgcn_exp2f(p1[r]); }
;     f32x16 sm = p0 + p1;
;     f32x2v s2 = (f32x2v){sm[0], sm[1]} + (f32x2v){sm[2], sm[3]};
; #pragma unroll
;     for (int r = 4; r < 16; r += 2) s2 += (f32x2v){sm[r], sm[r + 1]};
;     l_run = l_run * alpha + (s2[0] + s2[1]);
;     o0 = o0 * alpha; o1 = o1 * alpha;
.Lat_redo_A2:
	s_nop 15
	v_add_u32_e32 v1, s37, v222
	ds_read_b128 v[138:141], v1
	ds_read_b128 v[142:145], v1 offset:6656
	ds_read_b128 v[146:149], v1 offset:32
	ds_read_b128 v[150:153], v1 offset:6688
	ds_read_b128 v[154:157], v1 offset:64
	ds_read_b128 v[158:161], v1 offset:6720
	ds_read_b128 v[162:165], v1 offset:96
	ds_read_b128 v[166:169], v1 offset:6752
	s_waitcnt lgkmcnt(7)
	v_mfma_f32_32x32x16_bf16 v[34:49], v[138:141], v[114:117], v[98:113]
	ds_read_b128 v[138:141], v1 offset:128
	s_waitcnt lgkmcnt(7)
	v_mfma_f32_32x32x16_bf16 v[50:65], v[142:145], v[114:117], v[98:113]
	ds_read_b128 v[142:145], v1 offset:6784
	s_waitcnt lgkmcnt(7)
	v_mfma_f32_32x32x16_bf16 v[34:49], v[146:149], v[118:121], v[34:49]
	ds_read_b128 v[146:149], v1 offset:160
	s_waitcnt lgkmcnt(7)
	v_mfma_f32_32x32x16_bf16 v[50:65], v[150:153], v[118:121], v[50:65]
	ds_read_b128 v[150:153], v1 offset:6816
	s_waitcnt lgkmcnt(7)
	v_mfma_f32_32x32x16_bf16 v[34:49], v[154:157], v[122:125], v[34:49]
	s_waitcnt lgkmcnt(6)
	v_mfma_f32_32x32x16_bf16 v[50:65], v[158:161], v[122:125], v[50:65]
	s_waitcnt lgkmcnt(5)
	v_mfma_f32_32x32x16_bf16 v[34:49], v[162:165], v[126:129], v[34:49]
	s_waitcnt lgkmcnt(4)
	v_mfma_f32_32x32x16_bf16 v[50:65], v[166:169], v[126:129], v[50:65]
	s_waitcnt lgkmcnt(3)
	v_mfma_f32_32x32x16_bf16 v[34:49], v[138:141], v[130:133], v[34:49]
	s_waitcnt lgkmcnt(2)
	v_mfma_f32_32x32x16_bf16 v[50:65], v[142:145], v[130:133], v[50:65]
	s_waitcnt lgkmcnt(1)
	v_mfma_f32_32x32x16_bf16 v[34:49], v[146:149], v[134:137], v[34:49]
	s_waitcnt lgkmcnt(0)
	v_mfma_f32_32x32x16_bf16 v[50:65], v[150:153], v[134:137], v[50:65]
	s_branch .Lat_first_A2
.Lat_first_B2:
	s_nop 15
	v_max3_f32 v249, v66, v67, v68
	v_max3_f32 v1, v82, v83, v84
	v_max3_f32 v249, v249, v69, v70
	v_max3_f32 v1, v1, v85, v86
	v_max3_f32 v249, v249, v71, v72
	v_max3_f32 v1, v1, v87, v88
	v_max3_f32 v249, v249, v73, v74
	v_max3_f32 v1, v1, v89, v90
	v_max3_f32 v249, v249, v75, v76
	v_max3_f32 v1, v1, v91, v92
	v_max3_f32 v249, v249, v77, v78
	v_max3_f32 v1, v1, v93, v94
	v_max3_f32 v249, v249, v79, v80
	v_max3_f32 v1, v1, v95, v96
	v_max_f32_e32 v249, v249, v81
	v_max_f32_e32 v1, v1, v97
	v_max_f32_e32 v249, v249, v1
	v_mov_b32_e32 v1, v249
	s_nop 1
	v_permlane32_swap_b32_e32 v249, v1
	v_max_f32_e32 v249, v249, v1
	v_max_f32_e32 v250, s27, v249
	v_add_f32_e32 v248, v248, v250
	v_sub_f32_e32 v251, 0, v248
	v_mov_b32_e32 v98, v251
	v_mov_b32_e32 v99, v251
	v_mov_b32_e32 v100, v251
	v_mov_b32_e32 v101, v251
	v_mov_b32_e32 v102, v251
	v_mov_b32_e32 v103, v251
	v_mov_b32_e32 v104, v251
	v_mov_b32_e32 v105, v251
	v_mov_b32_e32 v106, v251
	v_mov_b32_e32 v107, v251
	v_mov_b32_e32 v108, v251
	v_mov_b32_e32 v109, v251
	v_mov_b32_e32 v110, v251
	v_mov_b32_e32 v111, v251
	v_mov_b32_e32 v112, v251
	v_mov_b32_e32 v113, v251
	v_sub_f32_e32 v66, v66, v250
	v_sub_f32_e32 v67, v67, v250
	v_sub_f32_e32 v68, v68, v250
	v_sub_f32_e32 v69, v69, v250
	v_sub_f32_e32 v70, v70, v250
	v_sub_f32_e32 v71, v71, v250
	v_sub_f32_e32 v72, v72, v250
	v_sub_f32_e32 v73, v73, v250
	v_sub_f32_e32 v74, v74, v250
	v_sub_f32_e32 v75, v75, v250
	v_sub_f32_e32 v76, v76, v250
	v_sub_f32_e32 v77, v77, v250
	v_sub_f32_e32 v78, v78, v250
	v_sub_f32_e32 v79, v79, v250
	v_sub_f32_e32 v80, v80, v250
	v_sub_f32_e32 v81, v81, v250
	v_sub_f32_e32 v82, v82, v250
	v_sub_f32_e32 v83, v83, v250
	v_sub_f32_e32 v84, v84, v250
	v_sub_f32_e32 v85, v85, v250
	v_sub_f32_e32 v86, v86, v250
	v_sub_f32_e32 v87, v87, v250
	v_sub_f32_e32 v88, v88, v250
	v_sub_f32_e32 v89, v89, v250
	v_sub_f32_e32 v90, v90, v250
	v_sub_f32_e32 v91, v91, v250
	v_sub_f32_e32 v92, v92, v250
	v_sub_f32_e32 v93, v93, v250
	v_sub_f32_e32 v94, v94, v250
	v_sub_f32_e32 v95, v95, v250
	v_sub_f32_e32 v96, v96, v250
	v_sub_f32_e32 v97, v97, v250
	v_sub_f32_e32 v252, 0, v250
	v_min_f32_e32 v252, 0x42800000, v252
	v_exp_f32_e32 v252, v252
	s_mov_b32 s7, 0
	s_mov_b32 s27, 0
	v_mul_f32_e32 v227, v227, v252
	v_mul_f32_e32 v2, v2, v252
	v_mul_f32_e32 v3, v3, v252
	v_mul_f32_e32 v4, v4, v252
	v_mul_f32_e32 v5, v5, v252
	v_mul_f32_e32 v6, v6, v252
	v_mul_f32_e32 v7, v7, v252
	v_mul_f32_e32 v8, v8, v252
	v_mul_f32_e32 v9, v9, v252
	v_mul_f32_e32 v10, v10, v252
	v_mul_f32_e32 v11, v11, v252
	v_mul_f32_e32 v12, v12, v252
	v_mul_f32_e32 v13, v13, v252
	v_mul_f32_e32 v14, v14, v252
	v_mul_f32_e32 v15, v15, v252
	v_mul_f32_e32 v16, v16, v252
	v_mul_f32_e32 v17, v17, v252
	v_mul_f32_e32 v18, v18, v252
	v_mul_f32_e32 v19, v19, v252
	v_mul_f32_e32 v20, v20, v252
	v_mul_f32_e32 v21, v21, v252
	v_mul_f32_e32 v22, v22, v252
	v_mul_f32_e32 v23, v23, v252
	v_mul_f32_e32 v24, v24, v252
	v_mul_f32_e32 v25, v25, v252
	v_mul_f32_e32 v26, v26, v252
	v_mul_f32_e32 v27, v27, v252
	v_mul_f32_e32 v28, v28, v252
	v_mul_f32_e32 v29, v29, v252
	v_mul_f32_e32 v30, v30, v252
	v_mul_f32_e32 v31, v31, v252
	v_mul_f32_e32 v32, v32, v252
	v_mul_f32_e32 v33, v33, v252
	s_nop 1
	s_branch .Lat_exp_B2
; __device__ __forceinline__ float max3f(float a, float b, float c) { return fmaxf(fmaxf(a, b), c); }
; __device__ __forceinline__ void attn_qk(f32x16& p0, f32x16& p1, const bf16x8 (&kf)[12], const bf16x8 (&qf)[6]) {
;     const f32x16 zero = {0.f, 0.f, 0.f, 0.f, 0.f, 0.f, 0.f, 0.f, 0.f, 0.f, 0.f, 0.f, 0.f, 0.f, 0.f, 0.f};
; #pragma unroll
;     for (int ks = 0; ks < 6; ++ks) {
;         p0 = __builtin_amdgcn_mfma_f32_32x32x16_bf16(kf[2 * ks], qf[ks], ks == 0 ? zero : p0, 0, 0, 0);
;         p1 = __builtin_amdgcn_mfma_f32_32x32x16_bf16(kf[2 * ks + 1], qf[ks], ks == 0 ? zero : p1, 0, 0, 0);
;     }
; __device__ __forceinline__ void attn_softmax(f32x16& p0, f32x16& p1, bf16x8 (&pb)[4], f32x16& o0, f32x16& o1, float& m_run, float& l_run) {
;     float mx = max3f(p0[0], p0[1], p1[0]), my = max3f(p0[2], p0[3], p1[1]);
;     mx = max3f(mx, p1[2], p1[3]);
; #pragma unroll
;     for (int r = 4; r < 16; r += 4) { mx = max3f(mx, p0[r], p0[r + 1]); my = max3f(my, p0[r + 2], p0[r + 3]); mx = max3f(mx, p1[r], p1[r + 1]); my = max3f(my, p1[r + 2], p1[r + 3]); }
;     mx = fmaxf(mx, my);
;     { auto rr = __builtin_amdgcn_permlane32_swap(__float_as_uint(mx), __float_as_uint(mx), false, false); mx = fmaxf(__uint_as_float(rr[0]), __uint_as_float(rr[1])); }
;     const float m_new = fmaxf(m_run, mx);
;     const float alpha = __builtin_amdgcn_exp2f(m_run - m_new);
;     m_run = m_new;
;     p0 = p0 - m_new; p1 = p1 - m_new;
; #pragma unroll
;     for (int r = 0; r < 16; ++r) { p0[r] = __builtin_amdgcn_exp2f(p0[r]); p1[r] = __builtin_amdgcn_exp2f(p1[r]); }
;     f32x16 sm = p0 + p1;
;     f32x2v s2 = (f32x2v){sm[0], sm[1]} + (f32x2v){sm[2], sm[3]};
; #pragma unroll
;     for (int r = 4; r < 16; r += 2) s2 += (f32x2v){sm[r], sm[r + 1]};
;     l_run = l_run * alpha + (s2[0] + s2[1]);
;     o0 = o0 * alpha; o1 = o1 * alpha;
.Lat_rare_B2:
	s_nop 15
	v_cmp_lt_f32_e32 vcc, 0x71800000, v1
	s_cbranch_vccnz .Lat_redo_B2
	v_frexp_exp_i32_f32_e32 v250, v1
	v_max_i32_e32 v250, 0, v250
	v_mov_b32_e32 v251, v250
	s_nop 1
	v_permlane32_swap_b32_e32 v250, v251
	v_max_i32_e32 v250, v250, v251
	v_sub_u32_e32 v251, 0, v250
	v_ldexp_f32 v66, v66, v251
	v_ldexp_f32 v67, v67, v251
	v_ldexp_f32 v68, v68, v251
	v_ldexp_f32 v69, v69, v251
	v_ldexp_f32 v70, v70, v251
	v_ldexp_f32 v71, v71, v251
	v_ldexp_f32 v72, v72, v251
	v_ldexp_f32 v73, v73, v251
	v_ldexp_f32 v74, v74, v251
	v_ldexp_f32 v75, v75, v251
	v_ldexp_f32 v76, v76, v251
	v_ldexp_f32 v77, v77, v251
	v_ldexp_f32 v78, v78, v251
	v_ldexp_f32 v79, v79, v251
	v_ldexp_f32 v80, v80, v251
	v_ldexp_f32 v81, v81, v251
	v_ldexp_f32 v82, v82, v251
	v_ldexp_f32 v83, v83, v251
	v_ldexp_f32 v84, v84, v251
	v_ldexp_f32 v85, v85, v251
	v_ldexp_f32 v86, v86, v251
	v_ldexp_f32 v87, v87, v251
	v_ldexp_f32 v88, v88, v251
	v_ldexp_f32 v89, v89, v251
	v_ldexp_f32 v90, v90, v251
	v_ldexp_f32 v91, v91, v251
	v_ldexp_f32 v92, v92, v251
	v_ldexp_f32 v93, v93, v251
	v_ldexp_f32 v94, v94, v251
	v_ldexp_f32 v95, v95, v251
	v_ldexp_f32 v96, v96, v251
	v_ldexp_f32 v97, v97, v251
	v_ldexp_f32 v1, v1, v251
	v_ldexp_f32 v227, v227, v251
	v_ldexp_f32 v2, v2, v251
	v_ldexp_f32 v3, v3, v251
	v_ldexp_f32 v4, v4, v251
	v_ldexp_f32 v5, v5, v251
	v_ldexp_f32 v6, v6, v251
	v_ldexp_f32 v7, v7, v251
	v_ldexp_f32 v8, v8, v251
	v_ldexp_f32 v9, v9, v251
	v_ldexp_f32 v10, v10, v251
	v_ldexp_f32 v11, v11, v251
	v_ldexp_f32 v12, v12, v251
	v_ldexp_f32 v13, v13, v251
	v_ldexp_f32 v14, v14, v251
	v_ldexp_f32 v15, v15, v251
	v_ldexp_f32 v16, v16, v251
	v_ldexp_f32 v17, v17, v251
	v_ldexp_f32 v18, v18, v251
	v_ldexp_f32 v19, v19, v251
	v_ldexp_f32 v20, v20, v251
	v_ldexp_f32 v21, v21, v251
	v_ldexp_f32 v22, v22, v251
	v_ldexp_f32 v23, v23, v251
	v_ldexp_f32 v24, v24, v251
	v_ldexp_f32 v25, v25, v251
	v_ldexp_f32 v26, v26, v251
	v_ldexp_f32 v27, v27, v251
	v_ldexp_f32 v28, v28, v251
	v_ldexp_f32 v29, v29, v251
	v_ldexp_f32 v30, v30, v251
	v_ldexp_f32 v31, v31, v251
	v_ldexp_f32 v32, v32, v251
	v_ldexp_f32 v33, v33, v251
	v_cvt_f32_i32_e32 v252, v250
	v_add_f32_e32 v248, v248, v252
	v_sub_f32_e32 v253, 0, v248
	v_mov_b32_e32 v98, v253
	v_mov_b32_e32 v99, v253
	v_mov_b32_e32 v100, v253
	v_mov_b32_e32 v101, v253
	v_mov_b32_e32 v102, v253
	v_mov_b32_e32 v103, v253
	v_mov_b32_e32 v104, v253
	v_mov_b32_e32 v105, v253
	v_mov_b32_e32 v106, v253
	v_mov_b32_e32 v107, v253
	v_mov_b32_e32 v108, v253
	v_mov_b32_e32 v109, v253
	v_mov_b32_e32 v110, v253
	v_mov_b32_e32 v111, v253
	v_mov_b32_e32 v112, v253
	v_mov_b32_e32 v113, v253
	s_nop 1
	s_branch .Lat_fast_B2
.Lat_redo_B2:
	s_nop 15
	v_add_u32_e32 v1, s37, v222
	ds_read_b128 v[154:157], v1 offset:13312
	ds_read_b128 v[158:161], v1 offset:19968
	ds_read_b128 v[162:165], v1 offset:13344
	ds_read_b128 v[166:169], v1 offset:20000
	ds_read_b128 v[138:141], v1 offset:13376
	ds_read_b128 v[142:145], v1 offset:20032
	ds_read_b128 v[146:149], v1 offset:13408
	ds_read_b128 v[150:153], v1 offset:20064
	s_waitcnt lgkmcnt(7)
	v_mfma_f32_32x32x16_bf16 v[66:81], v[154:157], v[114:117], v[98:113]
	ds_read_b128 v[154:157], v1 offset:13440
	s_waitcnt lgkmcnt(7)
	v_mfma_f32_32x32x16_bf16 v[82:97], v[158:161], v[114:117], v[98:113]
	ds_read_b128 v[158:161], v1 offset:20096
	s_waitcnt lgkmcnt(7)
	v_mfma_f32_32x32x16_bf16 v[66:81], v[162:165], v[118:121], v[66:81]
	ds_read_b128 v[162:165], v1 offset:13472
	s_waitcnt lgkmcnt(7)
	v_mfma_f32_32x32x16_bf16 v[82:97], v[166:169], v[118:121], v[82:97]
	ds_read_b128 v[166:169], v1 offset:20128
	s_waitcnt lgkmcnt(7)
	v_mfma_f32_32x32x16_bf16 v[66:81], v[138:141], v[122:125], v[66:81]
	s_waitcnt lgkmcnt(6)
	v_mfma_f32_32x32x16_bf16 v[82:97], v[142:145], v[122:125], v[82:97]
	s_waitcnt lgkmcnt(5)
	v_mfma_f32_32x32x16_bf16 v[66:81], v[146:149], v[126:129], v[66:81]
	s_waitcnt lgkmcnt(4)
	v_mfma_f32_32x32x16_bf16 v[82:97], v[150:153], v[126:129], v[82:97]
	s_waitcnt lgkmcnt(3)
	v_mfma_f32_32x32x16_bf16 v[66:81], v[154:157], v[130:133], v[66:81]
	s_waitcnt lgkmcnt(2)
	v_mfma_f32_32x32x16_bf16 v[82:97], v[158:161], v[130:133], v[82:97]
	s_waitcnt lgkmcnt(1)
	v_mfma_f32_32x32x16_bf16 v[66:81], v[162:165], v[134:137], v[66:81]
	s_waitcnt lgkmcnt(0)
	v_mfma_f32_32x32x16_bf16 v[82:97], v[166:169], v[134:137], v[82:97]
	s_branch .Lat_first_B2
; __device__ __forceinline__ float max3f(float a, float b, float c) { return fmaxf(fmaxf(a, b), c); }
; __device__ __forceinline__ void attn_softmax(f32x16& p0, f32x16& p1, bf16x8 (&pb)[4], f32x16& o0, f32x16& o1, float& m_run, float& l_run) {
;     float mx = max3f(p0[0], p0[1], p1[0]), my = max3f(p0[2], p0[3], p1[1]);
;     mx = max3f(mx, p1[2], p1[3]);
; #pragma unroll
;     for (int r = 4; r < 16; r += 4) { mx = max3f(mx, p0[r], p0[r + 1]); my = max3f(my, p0[r + 2], p0[r + 3]); mx = max3f(mx, p1[r], p1[r + 1]); my = max3f(my, p1[r + 2], p1[r + 3]); }
;     mx = fmaxf(mx, my);
;     { auto rr = __builtin_amdgcn_permlane32_swap(__float_as_uint(mx), __float_as_uint(mx), false, false); mx = fmaxf(__uint_as_float(rr[0]), __uint_as_float(rr[1])); }
;     const float m_new = fmaxf(m_run, mx);
;     const float alpha = __builtin_amdgcn_exp2f(m_run - m_new);
;     m_run = m_new;
;     p0 = p0 - m_new; p1 = p1 - m_new;
; #pragma unroll
;     for (int r = 0; r < 16; ++r) { p0[r] = __builtin_amdgcn_exp2f(p0[r]); p1[r] = __builtin_amdgcn_exp2f(p1[r]); }
;     f32x16 sm = p0 + p1;
;     f32x2v s2 = (f32x2v){sm[0], sm[1]} + (f32x2v){sm[2], sm[3]};
; #pragma unroll
;     for (int r = 4; r < 16; r += 2) s2 += (f32x2v){sm[r], sm[r + 1]};
;     l_run = l_run * alpha + (s2[0] + s2[1]);
;     o0 = o0 * alpha; o1 = o1 * alpha;
.Lat_first_A1:
	s_nop 15
	v_max3_f32 v249, v34, v35, v36
	v_max3_f32 v1, v50, v51, v52
	v_max3_f32 v249, v249, v37, v38
	v_max3_f32 v1, v1, v53, v54
	v_max3_f32 v249, v249, v39, v40
	v_max3_f32 v1, v1, v55, v56
	v_max3_f32 v249, v249, v41, v42
	v_max3_f32 v1, v1, v57, v58
	v_max3_f32 v249, v249, v43, v44
	v_max3_f32 v1, v1, v59, v60
	v_max3_f32 v249, v249, v45, v46
	v_max3_f32 v1, v1, v61, v62
	v_max3_f32 v249, v249, v47, v48
	v_max3_f32 v1, v1, v63, v64
	v_max_f32_e32 v249, v249, v49
	v_max_f32_e32 v1, v1, v65
	v_max_f32_e32 v249, v249, v1
	v_mov_b32_e32 v1, v249
	s_nop 1
	v_permlane32_swap_b32_e32 v249, v1
	v_max_f32_e32 v249, v249, v1
	v_max_f32_e32 v250, s27, v249
	v_add_f32_e32 v248, v248, v250
	v_sub_f32_e32 v251, 0, v248
	v_mov_b32_e32 v98, v251
	v_mov_b32_e32 v99, v251
	v_mov_b32_e32 v100, v251
	v_mov_b32_e32 v101, v251
	v_mov_b32_e32 v102, v251
	v_mov_b32_e32 v103, v251
	v_mov_b32_e32 v104, v251
	v_mov_b32_e32 v105, v251
	v_mov_b32_e32 v106, v251
	v_mov_b32_e32 v107, v251
	v_mov_b32_e32 v108, v251
	v_mov_b32_e32 v109, v251
	v_mov_b32_e32 v110, v251
	v_mov_b32_e32 v111, v251
	v_mov_b32_e32 v112, v251
	v_mov_b32_e32 v113, v251
	v_sub_f32_e32 v34, v34, v250
	v_sub_f32_e32 v35, v35, v250
	v_sub_f32_e32 v36, v36, v250
	v_sub_f32_e32 v37, v37, v250
	v_sub_f32_e32 v38, v38, v250
	v_sub_f32_e32 v39, v39, v250
	v_sub_f32_e32 v40, v40, v250
	v_sub_f32_e32 v41, v41, v250
	v_sub_f32_e32 v42, v42, v250
	v_sub_f32_e32 v43, v43, v250
	v_sub_f32_e32 v44, v44, v250
	v_sub_f32_e32 v45, v45, v250
	v_sub_f32_e32 v46, v46, v250
	v_sub_f32_e32 v47, v47, v250
	v_sub_f32_e32 v48, v48, v250
	v_sub_f32_e32 v49, v49, v250
	v_sub_f32_e32 v50, v50, v250
	v_sub_f32_e32 v51, v51, v250
	v_sub_f32_e32 v52, v52, v250
	v_sub_f32_e32 v53, v53, v250
	v_sub_f32_e32 v54, v54, v250
	v_sub_f32_e32 v55, v55, v250
	v_sub_f32_e32 v56, v56, v250
	v_sub_f32_e32 v57, v57, v250
	v_sub_f32_e32 v58, v58, v250
	v_sub_f32_e32 v59, v59, v250
	v_sub_f32_e32 v60, v60, v250
	v_sub_f32_e32 v61, v61, v250
	v_sub_f32_e32 v62, v62, v250
	v_sub_f32_e32 v63, v63, v250
	v_sub_f32_e32 v64, v64, v250
	v_sub_f32_e32 v65, v65, v250
	v_sub_f32_e32 v252, 0, v250
	v_min_f32_e32 v252, 0x42800000, v252
	v_exp_f32_e32 v252, v252
	s_mov_b32 s7, 0
	s_mov_b32 s27, 0
	v_mul_f32_e32 v227, v227, v252
	v_mul_f32_e32 v2, v2, v252
	v_mul_f32_e32 v3, v3, v252
	v_mul_f32_e32 v4, v4, v252
	v_mul_f32_e32 v5, v5, v252
	v_mul_f32_e32 v6, v6, v252
	v_mul_f32_e32 v7, v7, v252
	v_mul_f32_e32 v8, v8, v252
	v_mul_f32_e32 v9, v9, v252
	v_mul_f32_e32 v10, v10, v252
	v_mul_f32_e32 v11, v11, v252
	v_mul_f32_e32 v12, v12, v252
	v_mul_f32_e32 v13, v13, v252
	v_mul_f32_e32 v14, v14, v252
	v_mul_f32_e32 v15, v15, v252
	v_mul_f32_e32 v16, v16, v252
	v_mul_f32_e32 v17, v17, v252
	v_mul_f32_e32 v18, v18, v252
	v_mul_f32_e32 v19, v19, v252
	v_mul_f32_e32 v20, v20, v252
	v_mul_f32_e32 v21, v21, v252
	v_mul_f32_e32 v22, v22, v252
	v_mul_f32_e32 v23, v23, v252
	v_mul_f32_e32 v24, v24, v252
	v_mul_f32_e32 v25, v25, v252
	v_mul_f32_e32 v26, v26, v252
	v_mul_f32_e32 v27, v27, v252
	v_mul_f32_e32 v28, v28, v252
	v_mul_f32_e32 v29, v29, v252
	v_mul_f32_e32 v30, v30, v252
	v_mul_f32_e32 v31, v31, v252
	v_mul_f32_e32 v32, v32, v252
	v_mul_f32_e32 v33, v33, v252
	s_nop 1
	s_branch .Lat_exp_A1
.Lat_rare_A1:
	s_nop 15
	v_cmp_lt_f32_e32 vcc, 0x71800000, v1
	s_cbranch_vccnz .Lat_redo_A1
	v_frexp_exp_i32_f32_e32 v250, v1
	v_max_i32_e32 v250, 0, v250
	v_mov_b32_e32 v251, v250
	s_nop 1
	v_permlane32_swap_b32_e32 v250, v251
	v_max_i32_e32 v250, v250, v251
	v_sub_u32_e32 v251, 0, v250
	v_ldexp_f32 v34, v34, v251
	v_ldexp_f32 v35, v35, v251
	v_ldexp_f32 v36, v36, v251
	v_ldexp_f32 v37, v37, v251
	v_ldexp_f32 v38, v38, v251
	v_ldexp_f32 v39, v39, v251
	v_ldexp_f32 v40, v40, v251
	v_ldexp_f32 v41, v41, v251
	v_ldexp_f32 v42, v42, v251
	v_ldexp_f32 v43, v43, v251
	v_ldexp_f32 v44, v44, v251
	v_ldexp_f32 v45, v45, v251
	v_ldexp_f32 v46, v46, v251
	v_ldexp_f32 v47, v47, v251
	v_ldexp_f32 v48, v48, v251
	v_ldexp_f32 v49, v49, v251
	v_ldexp_f32 v50, v50, v251
	v_ldexp_f32 v51, v51, v251
	v_ldexp_f32 v52, v52, v251
	v_ldexp_f32 v53, v53, v251
	v_ldexp_f32 v54, v54, v251
	v_ldexp_f32 v55, v55, v251
	v_ldexp_f32 v56, v56, v251
	v_ldexp_f32 v57, v57, v251
	v_ldexp_f32 v58, v58, v251
	v_ldexp_f32 v59, v59, v251
	v_ldexp_f32 v60, v60, v251
	v_ldexp_f32 v61, v61, v251
	v_ldexp_f32 v62, v62, v251
	v_ldexp_f32 v63, v63, v251
	v_ldexp_f32 v64, v64, v251
	v_ldexp_f32 v65, v65, v251
	v_ldexp_f32 v1, v1, v251
	v_ldexp_f32 v227, v227, v251
	v_ldexp_f32 v2, v2, v251
	v_ldexp_f32 v3, v3, v251
	v_ldexp_f32 v4, v4, v251
	v_ldexp_f32 v5, v5, v251
	v_ldexp_f32 v6, v6, v251
	v_ldexp_f32 v7, v7, v251
	v_ldexp_f32 v8, v8, v251
	v_ldexp_f32 v9, v9, v251
	v_ldexp_f32 v10, v10, v251
	v_ldexp_f32 v11, v11, v251
	v_ldexp_f32 v12, v12, v251
	v_ldexp_f32 v13, v13, v251
	v_ldexp_f32 v14, v14, v251
	v_ldexp_f32 v15, v15, v251
	v_ldexp_f32 v16, v16, v251
	v_ldexp_f32 v17, v17, v251
	v_ldexp_f32 v18, v18, v251
	v_ldexp_f32 v19, v19, v251
	v_ldexp_f32 v20, v20, v251
	v_ldexp_f32 v21, v21, v251
	v_ldexp_f32 v22, v22, v251
	v_ldexp_f32 v23, v23, v251
	v_ldexp_f32 v24, v24, v251
	v_ldexp_f32 v25, v25, v251
	v_ldexp_f32 v26, v26, v251
	v_ldexp_f32 v27, v27, v251
	v_ldexp_f32 v28, v28, v251
	v_ldexp_f32 v29, v29, v251
	v_ldexp_f32 v30, v30, v251
	v_ldexp_f32 v31, v31, v251
	v_ldexp_f32 v32, v32, v251
	v_ldexp_f32 v33, v33, v251
	v_cvt_f32_i32_e32 v252, v250
	v_add_f32_e32 v248, v248, v252
	v_sub_f32_e32 v253, 0, v248
	v_mov_b32_e32 v98, v253
	v_mov_b32_e32 v99, v253
	v_mov_b32_e32 v100, v253
	v_mov_b32_e32 v101, v253
	v_mov_b32_e32 v102, v253
	v_mov_b32_e32 v103, v253
	v_mov_b32_e32 v104, v253
	v_mov_b32_e32 v105, v253
	v_mov_b32_e32 v106, v253
	v_mov_b32_e32 v107, v253
	v_mov_b32_e32 v108, v253
	v_mov_b32_e32 v109, v253
	v_mov_b32_e32 v110, v253
	v_mov_b32_e32 v111, v253
	v_mov_b32_e32 v112, v253
	v_mov_b32_e32 v113, v253
	s_nop 1
	s_branch .Lat_fast_A1

; __device__ __forceinline__ void attn_softmax(f32x16& p0, f32x16& p1, bf16x8 (&pb)[4], f32x16& o0, f32x16& o1, float& m_run, float& l_run) {
;     ...
;     const float m_new = fmaxf(m_run, mx);
;     const float alpha = __builtin_amdgcn_exp2f(m_run - m_new);
;     m_run = m_new;
;     p0 = p0 - m_new; p1 = p1 - m_new;
.Lat_fix_B:
	s_nop 15
	s_mov_b32 s6, 0
	v_sub_f32_e32 v66, v66, v218
	v_sub_f32_e32 v67, v67, v218
	v_sub_f32_e32 v68, v68, v218
	v_sub_f32_e32 v69, v69, v218
	v_sub_f32_e32 v70, v70, v218
	v_sub_f32_e32 v71, v71, v218
	v_sub_f32_e32 v72, v72, v218
	v_sub_f32_e32 v73, v73, v218
	v_sub_f32_e32 v74, v74, v218
	v_sub_f32_e32 v75, v75, v218
	v_sub_f32_e32 v76, v76, v218
	v_sub_f32_e32 v77, v77, v218
	v_sub_f32_e32 v78, v78, v218
	v_sub_f32_e32 v79, v79, v218
	v_sub_f32_e32 v80, v80, v218
	v_sub_f32_e32 v81, v81, v218
	v_sub_f32_e32 v82, v82, v218
	v_sub_f32_e32 v83, v83, v218
	v_sub_f32_e32 v84, v84, v218
	v_sub_f32_e32 v85, v85, v218
	v_sub_f32_e32 v86, v86, v218
	v_sub_f32_e32 v87, v87, v218
	v_sub_f32_e32 v88, v88, v218
	v_sub_f32_e32 v89, v89, v218
	v_sub_f32_e32 v90, v90, v218
	v_sub_f32_e32 v91, v91, v218
	v_sub_f32_e32 v92, v92, v218
	v_sub_f32_e32 v93, v93, v218
	v_sub_f32_e32 v94, v94, v218
	v_sub_f32_e32 v95, v95, v218
	v_sub_f32_e32 v96, v96, v218
	v_sub_f32_e32 v97, v97, v218
	s_branch .Lat_fixed_B
